# FoX pair loop: cross-half row max / row sum via v_permlane32_swap instead of ds_bpermute (no LDS round trip on the long waves' critical path)
# baseline (speedup 1.0000x reference)
.Lfox_loop:
	s_waitcnt vmcnt(4)
	v_mfma_f32_32x32x16_bf16 v[138:153], v[2:5], v[38:41], 0
	v_mfma_f32_32x32x16_bf16 v[138:153], v[6:9], v[42:45], v[138:153]
	v_mfma_f32_32x32x16_bf16 v[138:153], v[10:13], v[46:49], v[138:153]
	v_mfma_f32_32x32x16_bf16 v[138:153], v[14:17], v[50:53], v[138:153]
	v_mfma_f32_32x32x16_bf16 v[138:153], v[18:21], v[70:73], v[138:153]
	v_mfma_f32_32x32x16_bf16 v[154:169], v[2:5], v[54:57], 0
	s_nop 7
	s_nop 4
	v_max3_f32 v183, v138, v139, v140
	v_max3_f32 v184, v141, v142, v143
	v_max3_f32 v185, v144, v145, v146
	v_max3_f32 v186, v147, v148, v149
	v_max3_f32 v187, v150, v151, v152
	v_max3_f32 v183, v183, v184, v185
	v_max3_f32 v186, v186, v187, v153
	v_max_f32_e32 v183, v183, v186
	v_mov_b32_e32 v184, v183
	s_nop 1
	v_permlane32_swap_b32_e32 v184, v183
	v_max_f32_e32 v183, v183, v184
	v_fma_f32 v183, v183, s14, v199
	v_max_f32_e32 v184, v197, v183
	v_mfma_f32_32x32x16_bf16 v[154:169], v[6:9], v[58:61], v[154:169]
	v_sub_f32_e32 v186, v197, v184
	v_exp_f32_e32 v186, v186
	v_mov_b32_e32 v197, v184
	v_sub_f32_e32 v200, v199, v184
	v_fma_f32 v138, v138, s14, v200
	v_exp_f32_e32 v138, v138
	v_fma_f32 v139, v139, s14, v200
	v_exp_f32_e32 v139, v139
	v_fma_f32 v140, v140, s14, v200
	v_exp_f32_e32 v140, v140
	v_fma_f32 v141, v141, s14, v200
	v_exp_f32_e32 v141, v141
	v_fma_f32 v142, v142, s14, v200
	v_exp_f32_e32 v142, v142
	v_mfma_f32_32x32x16_bf16 v[154:169], v[10:13], v[62:65], v[154:169]
	v_fma_f32 v143, v143, s14, v200
	v_exp_f32_e32 v143, v143
	v_fma_f32 v144, v144, s14, v200
	v_exp_f32_e32 v144, v144
	v_fma_f32 v145, v145, s14, v200
	v_exp_f32_e32 v145, v145
	v_fma_f32 v146, v146, s14, v200
	v_exp_f32_e32 v146, v146
	v_fma_f32 v147, v147, s14, v200
	v_exp_f32_e32 v147, v147
	v_fma_f32 v148, v148, s14, v200
	v_exp_f32_e32 v148, v148
	v_fma_f32 v149, v149, s14, v200
	v_exp_f32_e32 v149, v149
	v_mfma_f32_32x32x16_bf16 v[154:169], v[14:17], v[66:69], v[154:169]
	v_fma_f32 v150, v150, s14, v200
	v_exp_f32_e32 v150, v150
	v_fma_f32 v151, v151, s14, v200
	v_exp_f32_e32 v151, v151
	v_fma_f32 v152, v152, s14, v200
	v_exp_f32_e32 v152, v152
	v_fma_f32 v153, v153, s14, v200
	v_exp_f32_e32 v153, v153
	v_mul_f32_e32 v198, v198, v186
	v_pk_mul_f32 v[74:75], v[74:75], v[186:187] op_sel_hi:[1,0]
	v_pk_mul_f32 v[76:77], v[76:77], v[186:187] op_sel_hi:[1,0]
	v_pk_mul_f32 v[78:79], v[78:79], v[186:187] op_sel_hi:[1,0]
	v_pk_mul_f32 v[80:81], v[80:81], v[186:187] op_sel_hi:[1,0]
	v_pk_mul_f32 v[82:83], v[82:83], v[186:187] op_sel_hi:[1,0]
	v_mfma_f32_32x32x16_bf16 v[154:169], v[18:21], v[70:73], v[154:169]
	s_add_i32 s18, s16, 1
	s_lshl_b32 s17, s18, 12
	v_add_u32_e32 v207, s17, v194
	global_load_dwordx4 v[2:5], v207, s[4:5]
	global_load_dwordx4 v[6:9], v207, s[4:5] offset:1024
	global_load_dwordx4 v[10:13], v207, s[4:5] offset:2048
	global_load_dwordx4 v[14:17], v207, s[4:5] offset:3072
	s_lshl_b32 s17, s18, 9
	v_add_u32_e32 v209, s17, v190
	s_mov_b64 exec, s[44:45]
	global_load_dwordx4 v[18:21], v209, s[8:9]
	s_mov_b64 exec, -1
	v_pk_mul_f32 v[84:85], v[84:85], v[186:187] op_sel_hi:[1,0]
	v_pk_mul_f32 v[86:87], v[86:87], v[186:187] op_sel_hi:[1,0]
	v_pk_mul_f32 v[88:89], v[88:89], v[186:187] op_sel_hi:[1,0]
	v_pk_mul_f32 v[90:91], v[90:91], v[186:187] op_sel_hi:[1,0]
	v_pk_mul_f32 v[92:93], v[92:93], v[186:187] op_sel_hi:[1,0]
	v_pk_mul_f32 v[94:95], v[94:95], v[186:187] op_sel_hi:[1,0]
	v_pk_mul_f32 v[96:97], v[96:97], v[186:187] op_sel_hi:[1,0]
	v_pk_mul_f32 v[98:99], v[98:99], v[186:187] op_sel_hi:[1,0]
	v_pk_mul_f32 v[100:101], v[100:101], v[186:187] op_sel_hi:[1,0]
	v_pk_mul_f32 v[102:103], v[102:103], v[186:187] op_sel_hi:[1,0]
	v_pk_mul_f32 v[104:105], v[104:105], v[186:187] op_sel_hi:[1,0]
	v_add_f32_e32 v183, v138, v139
	v_add_f32_e32 v184, v140, v141
	v_add_f32_e32 v185, v142, v143
	v_add_f32_e32 v188, v144, v145
	v_add_f32_e32 v183, v183, v146
	v_add_f32_e32 v184, v184, v147
	v_add_f32_e32 v185, v185, v148
	v_add_f32_e32 v188, v188, v149
	v_add_f32_e32 v183, v183, v150
	v_add_f32_e32 v184, v184, v151
	v_add_f32_e32 v185, v185, v152
	v_add_f32_e32 v188, v188, v153
	v_add_f32_e32 v183, v183, v184
	v_add_f32_e32 v185, v185, v188
	v_add_f32_e32 v183, v183, v185
	v_add_f32_e32 v198, v198, v183
	v_cvt_pk_bf16_f32 v138, v138, v139
	v_cvt_pk_bf16_f32 v139, v140, v141
	v_cvt_pk_bf16_f32 v140, v142, v143
	v_cvt_pk_bf16_f32 v141, v144, v145
	v_cvt_pk_bf16_f32 v142, v146, v147
	v_cvt_pk_bf16_f32 v143, v148, v149
	v_cvt_pk_bf16_f32 v144, v150, v151
	v_cvt_pk_bf16_f32 v145, v152, v153
	v_max3_f32 v183, v154, v155, v156
	v_max3_f32 v184, v157, v158, v159
	v_max3_f32 v185, v160, v161, v162
	s_waitcnt vmcnt(5)
	v_mfma_f32_32x32x16_bf16 v[74:89], v[22:25], v[138:141], v[74:89]
	v_max3_f32 v186, v163, v164, v165
	v_max3_f32 v187, v166, v167, v168
	v_max3_f32 v183, v183, v184, v185
	v_mfma_f32_32x32x16_bf16 v[90:105], v[30:33], v[138:141], v[90:105]
	v_max3_f32 v186, v186, v187, v169
	v_max_f32_e32 v183, v183, v186
	v_mov_b32_e32 v184, v183
	s_nop 1
	v_permlane32_swap_b32_e32 v184, v183
	v_max_f32_e32 v183, v183, v184
	v_fma_f32 v183, v183, s14, v203
	v_max_f32_e32 v184, v201, v183
	v_sub_f32_e32 v186, v201, v184
	v_exp_f32_e32 v186, v186
	v_mov_b32_e32 v201, v184
	v_sub_f32_e32 v204, v203, v184
	v_fma_f32 v154, v154, s14, v204
	v_exp_f32_e32 v154, v154
	v_fma_f32 v155, v155, s14, v204
	v_exp_f32_e32 v155, v155
	v_fma_f32 v156, v156, s14, v204
	v_exp_f32_e32 v156, v156
	v_fma_f32 v157, v157, s14, v204
	v_exp_f32_e32 v157, v157
	v_fma_f32 v158, v158, s14, v204
	v_exp_f32_e32 v158, v158
	v_fma_f32 v159, v159, s14, v204
	v_exp_f32_e32 v159, v159
	v_mfma_f32_32x32x16_bf16 v[74:89], v[26:29], v[142:145], v[74:89]
	v_fma_f32 v160, v160, s14, v204
	v_exp_f32_e32 v160, v160
	v_fma_f32 v161, v161, s14, v204
	v_exp_f32_e32 v161, v161
	v_mfma_f32_32x32x16_bf16 v[90:105], v[34:37], v[142:145], v[90:105]
	v_fma_f32 v162, v162, s14, v204
	v_exp_f32_e32 v162, v162
	v_fma_f32 v163, v163, s14, v204
	v_exp_f32_e32 v163, v163
	v_fma_f32 v164, v164, s14, v204
	v_exp_f32_e32 v164, v164
	v_fma_f32 v165, v165, s14, v204
	v_exp_f32_e32 v165, v165
	v_fma_f32 v166, v166, s14, v204
	v_exp_f32_e32 v166, v166
	v_fma_f32 v167, v167, s14, v204
	v_exp_f32_e32 v167, v167
	v_fma_f32 v168, v168, s14, v204
	v_exp_f32_e32 v168, v168
	v_fma_f32 v169, v169, s14, v204
	v_exp_f32_e32 v169, v169
	v_mul_f32_e32 v202, v202, v186
	v_pk_mul_f32 v[106:107], v[106:107], v[186:187] op_sel_hi:[1,0]
	v_pk_mul_f32 v[108:109], v[108:109], v[186:187] op_sel_hi:[1,0]
	v_pk_mul_f32 v[110:111], v[110:111], v[186:187] op_sel_hi:[1,0]
	v_pk_mul_f32 v[112:113], v[112:113], v[186:187] op_sel_hi:[1,0]
	v_pk_mul_f32 v[114:115], v[114:115], v[186:187] op_sel_hi:[1,0]
	v_pk_mul_f32 v[116:117], v[116:117], v[186:187] op_sel_hi:[1,0]
	v_pk_mul_f32 v[118:119], v[118:119], v[186:187] op_sel_hi:[1,0]
	v_pk_mul_f32 v[120:121], v[120:121], v[186:187] op_sel_hi:[1,0]
	v_pk_mul_f32 v[122:123], v[122:123], v[186:187] op_sel_hi:[1,0]
	v_pk_mul_f32 v[124:125], v[124:125], v[186:187] op_sel_hi:[1,0]
	v_pk_mul_f32 v[126:127], v[126:127], v[186:187] op_sel_hi:[1,0]
	v_pk_mul_f32 v[128:129], v[128:129], v[186:187] op_sel_hi:[1,0]
	v_pk_mul_f32 v[130:131], v[130:131], v[186:187] op_sel_hi:[1,0]
	v_pk_mul_f32 v[132:133], v[132:133], v[186:187] op_sel_hi:[1,0]
	v_pk_mul_f32 v[134:135], v[134:135], v[186:187] op_sel_hi:[1,0]
	v_pk_mul_f32 v[136:137], v[136:137], v[186:187] op_sel_hi:[1,0]
	v_add_f32_e32 v183, v154, v155
	v_add_f32_e32 v184, v156, v157
	v_add_f32_e32 v185, v158, v159
	v_add_f32_e32 v188, v160, v161
	v_add_f32_e32 v183, v183, v162
	v_add_f32_e32 v184, v184, v163
	v_add_f32_e32 v185, v185, v164
	v_add_f32_e32 v188, v188, v165
	v_add_f32_e32 v183, v183, v166
	v_add_f32_e32 v184, v184, v167
	v_add_f32_e32 v185, v185, v168
	v_add_f32_e32 v188, v188, v169
	v_add_f32_e32 v183, v183, v184
	v_add_f32_e32 v185, v185, v188
	v_add_f32_e32 v183, v183, v185
	v_add_f32_e32 v202, v202, v183
	v_cvt_pk_bf16_f32 v154, v154, v155
	v_cvt_pk_bf16_f32 v155, v156, v157
	v_cvt_pk_bf16_f32 v156, v158, v159
	v_cvt_pk_bf16_f32 v157, v160, v161
	v_cvt_pk_bf16_f32 v158, v162, v163
	v_cvt_pk_bf16_f32 v159, v164, v165
	v_cvt_pk_bf16_f32 v160, v166, v167
	v_cvt_pk_bf16_f32 v161, v168, v169
	s_nop 1
	v_mfma_f32_32x32x16_bf16 v[106:121], v[22:25], v[154:157], v[106:121]
	v_mfma_f32_32x32x16_bf16 v[122:137], v[30:33], v[154:157], v[122:137]
	v_mfma_f32_32x32x16_bf16 v[106:121], v[26:29], v[158:161], v[106:121]
	v_mfma_f32_32x32x16_bf16 v[122:137], v[34:37], v[158:161], v[122:137]
	s_lshl_b32 s17, s18, 12
	v_add_u32_e32 v208, s17, v194
	global_load_dwordx4 v[22:25], v208, s[6:7]
	global_load_dwordx4 v[26:29], v208, s[6:7] offset:1024
	global_load_dwordx4 v[30:33], v208, s[6:7] offset:2048
	global_load_dwordx4 v[34:37], v208, s[6:7] offset:3072
	s_add_i32 s16, s16, 1
	s_cmp_lt_u32 s16, s15
	s_cbranch_scc1 .Lfox_loop
.Lfox_tail:
	s_waitcnt vmcnt(4)
	v_mfma_f32_32x32x16_bf16 v[138:153], v[2:5], v[38:41], 0
	v_mfma_f32_32x32x16_bf16 v[138:153], v[6:9], v[42:45], v[138:153]
	v_mfma_f32_32x32x16_bf16 v[138:153], v[10:13], v[46:49], v[138:153]
	v_mfma_f32_32x32x16_bf16 v[138:153], v[14:17], v[50:53], v[138:153]
	v_mfma_f32_32x32x16_bf16 v[138:153], v[18:21], v[70:73], v[138:153]
	v_mfma_f32_32x32x16_bf16 v[154:169], v[2:5], v[54:57], 0
	s_nop 7
	s_nop 4
	v_cmp_le_i32_e64 s[34:35], 0, v170
	v_cmp_le_i32_e64 s[36:37], 1, v170
	v_cmp_le_i32_e64 s[38:39], 2, v170
	v_cmp_le_i32_e64 s[40:41], 3, v170
	v_cmp_le_i32_e32 vcc, 8, v170
	v_cndmask_b32_e64 v138, v193, v138, s[34:35]
	v_cndmask_b32_e64 v139, v193, v139, s[36:37]
	v_cndmask_b32_e64 v140, v193, v140, s[38:39]
	v_cndmask_b32_e64 v141, v193, v141, s[40:41]
	v_cndmask_b32_e64 v142, v193, v142, vcc
	v_cmp_le_i32_e64 s[34:35], 9, v170
	v_cmp_le_i32_e64 s[36:37], 10, v170
	v_cmp_le_i32_e64 s[38:39], 11, v170
	v_cmp_le_i32_e64 s[40:41], 16, v170
	v_cmp_le_i32_e32 vcc, 17, v170
	v_cndmask_b32_e64 v143, v193, v143, s[34:35]
	v_cndmask_b32_e64 v144, v193, v144, s[36:37]
	v_cndmask_b32_e64 v145, v193, v145, s[38:39]
	v_cndmask_b32_e64 v146, v193, v146, s[40:41]
	v_cndmask_b32_e64 v147, v193, v147, vcc
	v_cmp_le_i32_e64 s[34:35], 18, v170
	v_cmp_le_i32_e64 s[36:37], 19, v170
	v_cmp_le_i32_e64 s[38:39], 24, v170
	v_cmp_le_i32_e64 s[40:41], 25, v170
	v_cmp_le_i32_e32 vcc, 26, v170
	v_cndmask_b32_e64 v148, v193, v148, s[34:35]
	v_cndmask_b32_e64 v149, v193, v149, s[36:37]
	v_cndmask_b32_e64 v150, v193, v150, s[38:39]
	v_cndmask_b32_e64 v151, v193, v151, s[40:41]
	v_cndmask_b32_e64 v152, v193, v152, vcc
	v_cmp_le_i32_e64 s[34:35], 27, v170
	s_nop 1
	v_cndmask_b32_e64 v153, v193, v153, s[34:35]
	v_max3_f32 v183, v138, v139, v140
	v_max3_f32 v184, v141, v142, v143
	v_max3_f32 v185, v144, v145, v146
	v_max3_f32 v186, v147, v148, v149
	v_max3_f32 v187, v150, v151, v152
	v_max3_f32 v183, v183, v184, v185
	v_max3_f32 v186, v186, v187, v153
	v_max_f32_e32 v183, v183, v186
	v_mov_b32_e32 v184, v183
	s_nop 1
	v_permlane32_swap_b32_e32 v184, v183
	v_max_f32_e32 v183, v183, v184
	v_fma_f32 v183, v183, s14, v199
	v_max_f32_e32 v184, v197, v183
	v_mfma_f32_32x32x16_bf16 v[154:169], v[6:9], v[58:61], v[154:169]
	v_sub_f32_e32 v186, v197, v184
	v_exp_f32_e32 v186, v186
	v_mov_b32_e32 v197, v184
	v_sub_f32_e32 v200, v199, v184
	v_fma_f32 v138, v138, s14, v200
	v_exp_f32_e32 v138, v138
	v_fma_f32 v139, v139, s14, v200
	v_exp_f32_e32 v139, v139
	v_fma_f32 v140, v140, s14, v200
	v_exp_f32_e32 v140, v140
	v_fma_f32 v141, v141, s14, v200
	v_exp_f32_e32 v141, v141
	v_fma_f32 v142, v142, s14, v200
	v_exp_f32_e32 v142, v142
	v_mfma_f32_32x32x16_bf16 v[154:169], v[10:13], v[62:65], v[154:169]
	v_fma_f32 v143, v143, s14, v200
	v_exp_f32_e32 v143, v143
	v_fma_f32 v144, v144, s14, v200
	v_exp_f32_e32 v144, v144
	v_fma_f32 v145, v145, s14, v200
	v_exp_f32_e32 v145, v145
	v_fma_f32 v146, v146, s14, v200
	v_exp_f32_e32 v146, v146
	v_fma_f32 v147, v147, s14, v200
	v_exp_f32_e32 v147, v147
	v_fma_f32 v148, v148, s14, v200
	v_exp_f32_e32 v148, v148
	v_fma_f32 v149, v149, s14, v200
	v_exp_f32_e32 v149, v149
	v_mfma_f32_32x32x16_bf16 v[154:169], v[14:17], v[66:69], v[154:169]
	v_fma_f32 v150, v150, s14, v200
	v_exp_f32_e32 v150, v150
	v_fma_f32 v151, v151, s14, v200
	v_exp_f32_e32 v151, v151
	v_fma_f32 v152, v152, s14, v200
	v_exp_f32_e32 v152, v152
	v_fma_f32 v153, v153, s14, v200
	v_exp_f32_e32 v153, v153
	v_mul_f32_e32 v198, v198, v186
	v_pk_mul_f32 v[74:75], v[74:75], v[186:187] op_sel_hi:[1,0]
	v_pk_mul_f32 v[76:77], v[76:77], v[186:187] op_sel_hi:[1,0]
	v_pk_mul_f32 v[78:79], v[78:79], v[186:187] op_sel_hi:[1,0]
	v_pk_mul_f32 v[80:81], v[80:81], v[186:187] op_sel_hi:[1,0]
	v_pk_mul_f32 v[82:83], v[82:83], v[186:187] op_sel_hi:[1,0]
	v_mfma_f32_32x32x16_bf16 v[154:169], v[18:21], v[70:73], v[154:169]
	s_add_i32 s18, s16, 1
	s_lshl_b32 s17, s18, 12
	v_add_u32_e32 v207, s17, v194
	global_load_dwordx4 v[2:5], v207, s[4:5]
	global_load_dwordx4 v[6:9], v207, s[4:5] offset:1024
	global_load_dwordx4 v[10:13], v207, s[4:5] offset:2048
	global_load_dwordx4 v[14:17], v207, s[4:5] offset:3072
	s_lshl_b32 s17, s18, 9
	v_add_u32_e32 v209, s17, v190
	s_mov_b64 exec, s[44:45]
	global_load_dwordx4 v[18:21], v209, s[8:9]
	s_mov_b64 exec, -1
	v_pk_mul_f32 v[84:85], v[84:85], v[186:187] op_sel_hi:[1,0]
	v_pk_mul_f32 v[86:87], v[86:87], v[186:187] op_sel_hi:[1,0]
	v_pk_mul_f32 v[88:89], v[88:89], v[186:187] op_sel_hi:[1,0]
	v_pk_mul_f32 v[90:91], v[90:91], v[186:187] op_sel_hi:[1,0]
	v_pk_mul_f32 v[92:93], v[92:93], v[186:187] op_sel_hi:[1,0]
	v_pk_mul_f32 v[94:95], v[94:95], v[186:187] op_sel_hi:[1,0]
	v_pk_mul_f32 v[96:97], v[96:97], v[186:187] op_sel_hi:[1,0]
	v_pk_mul_f32 v[98:99], v[98:99], v[186:187] op_sel_hi:[1,0]
	v_pk_mul_f32 v[100:101], v[100:101], v[186:187] op_sel_hi:[1,0]
	v_pk_mul_f32 v[102:103], v[102:103], v[186:187] op_sel_hi:[1,0]
	v_pk_mul_f32 v[104:105], v[104:105], v[186:187] op_sel_hi:[1,0]
	v_add_f32_e32 v183, v138, v139
	v_add_f32_e32 v184, v140, v141
	v_add_f32_e32 v185, v142, v143
	v_add_f32_e32 v188, v144, v145
	v_add_f32_e32 v183, v183, v146
	v_add_f32_e32 v184, v184, v147
	v_add_f32_e32 v185, v185, v148
	v_add_f32_e32 v188, v188, v149
	v_add_f32_e32 v183, v183, v150
	v_add_f32_e32 v184, v184, v151
	v_add_f32_e32 v185, v185, v152
	v_add_f32_e32 v188, v188, v153
	v_add_f32_e32 v183, v183, v184
	v_add_f32_e32 v185, v185, v188
	v_add_f32_e32 v183, v183, v185
	v_add_f32_e32 v198, v198, v183
	v_cvt_pk_bf16_f32 v138, v138, v139
	v_cvt_pk_bf16_f32 v139, v140, v141
	v_cvt_pk_bf16_f32 v140, v142, v143
	v_cvt_pk_bf16_f32 v141, v144, v145
	v_cvt_pk_bf16_f32 v142, v146, v147
	v_cvt_pk_bf16_f32 v143, v148, v149
	v_cvt_pk_bf16_f32 v144, v150, v151
	v_cvt_pk_bf16_f32 v145, v152, v153
	v_max3_f32 v183, v154, v155, v156
	v_max3_f32 v184, v157, v158, v159
	v_max3_f32 v185, v160, v161, v162
	s_waitcnt vmcnt(5)
	v_mfma_f32_32x32x16_bf16 v[74:89], v[22:25], v[138:141], v[74:89]
	v_max3_f32 v186, v163, v164, v165
	v_max3_f32 v187, v166, v167, v168
	v_max3_f32 v183, v183, v184, v185
	v_mfma_f32_32x32x16_bf16 v[90:105], v[30:33], v[138:141], v[90:105]
	v_max3_f32 v186, v186, v187, v169
	v_max_f32_e32 v183, v183, v186
	v_mov_b32_e32 v184, v183
	s_nop 1
	v_permlane32_swap_b32_e32 v184, v183
	v_max_f32_e32 v183, v183, v184
	v_fma_f32 v183, v183, s14, v203
	v_max_f32_e32 v184, v201, v183
	v_sub_f32_e32 v186, v201, v184
	v_exp_f32_e32 v186, v186
	v_mov_b32_e32 v201, v184
	v_sub_f32_e32 v204, v203, v184
	v_fma_f32 v154, v154, s14, v204
	v_exp_f32_e32 v154, v154
	v_fma_f32 v155, v155, s14, v204
	v_exp_f32_e32 v155, v155
	v_fma_f32 v156, v156, s14, v204
	v_exp_f32_e32 v156, v156
	v_fma_f32 v157, v157, s14, v204
	v_exp_f32_e32 v157, v157
	v_fma_f32 v158, v158, s14, v204
	v_exp_f32_e32 v158, v158
	v_fma_f32 v159, v159, s14, v204
	v_exp_f32_e32 v159, v159
	v_mfma_f32_32x32x16_bf16 v[74:89], v[26:29], v[142:145], v[74:89]
	v_fma_f32 v160, v160, s14, v204
	v_exp_f32_e32 v160, v160
	v_fma_f32 v161, v161, s14, v204
	v_exp_f32_e32 v161, v161
	v_mfma_f32_32x32x16_bf16 v[90:105], v[34:37], v[142:145], v[90:105]
	v_fma_f32 v162, v162, s14, v204
	v_exp_f32_e32 v162, v162
	v_fma_f32 v163, v163, s14, v204
	v_exp_f32_e32 v163, v163
	v_fma_f32 v164, v164, s14, v204
	v_exp_f32_e32 v164, v164
	v_fma_f32 v165, v165, s14, v204
	v_exp_f32_e32 v165, v165
	v_fma_f32 v166, v166, s14, v204
	v_exp_f32_e32 v166, v166
	v_fma_f32 v167, v167, s14, v204
	v_exp_f32_e32 v167, v167
	v_fma_f32 v168, v168, s14, v204
	v_exp_f32_e32 v168, v168
	v_fma_f32 v169, v169, s14, v204
	v_exp_f32_e32 v169, v169
	v_mul_f32_e32 v202, v202, v186
	v_pk_mul_f32 v[106:107], v[106:107], v[186:187] op_sel_hi:[1,0]
	v_pk_mul_f32 v[108:109], v[108:109], v[186:187] op_sel_hi:[1,0]
	v_pk_mul_f32 v[110:111], v[110:111], v[186:187] op_sel_hi:[1,0]
	v_pk_mul_f32 v[112:113], v[112:113], v[186:187] op_sel_hi:[1,0]
	v_pk_mul_f32 v[114:115], v[114:115], v[186:187] op_sel_hi:[1,0]
	v_pk_mul_f32 v[116:117], v[116:117], v[186:187] op_sel_hi:[1,0]
	v_pk_mul_f32 v[118:119], v[118:119], v[186:187] op_sel_hi:[1,0]
	v_pk_mul_f32 v[120:121], v[120:121], v[186:187] op_sel_hi:[1,0]
	v_pk_mul_f32 v[122:123], v[122:123], v[186:187] op_sel_hi:[1,0]
	v_pk_mul_f32 v[124:125], v[124:125], v[186:187] op_sel_hi:[1,0]
	v_pk_mul_f32 v[126:127], v[126:127], v[186:187] op_sel_hi:[1,0]
	v_pk_mul_f32 v[128:129], v[128:129], v[186:187] op_sel_hi:[1,0]
	v_pk_mul_f32 v[130:131], v[130:131], v[186:187] op_sel_hi:[1,0]
	v_pk_mul_f32 v[132:133], v[132:133], v[186:187] op_sel_hi:[1,0]
	v_pk_mul_f32 v[134:135], v[134:135], v[186:187] op_sel_hi:[1,0]
	v_pk_mul_f32 v[136:137], v[136:137], v[186:187] op_sel_hi:[1,0]
	v_add_f32_e32 v183, v154, v155
	v_add_f32_e32 v184, v156, v157
	v_add_f32_e32 v185, v158, v159
	v_add_f32_e32 v188, v160, v161
	v_add_f32_e32 v183, v183, v162
	v_add_f32_e32 v184, v184, v163
	v_add_f32_e32 v185, v185, v164
	v_add_f32_e32 v188, v188, v165
	v_add_f32_e32 v183, v183, v166
	v_add_f32_e32 v184, v184, v167
	v_add_f32_e32 v185, v185, v168
	v_add_f32_e32 v188, v188, v169
	v_add_f32_e32 v183, v183, v184
	v_add_f32_e32 v185, v185, v188
	v_add_f32_e32 v183, v183, v185
	v_add_f32_e32 v202, v202, v183
	v_cvt_pk_bf16_f32 v154, v154, v155
	v_cvt_pk_bf16_f32 v155, v156, v157
	v_cvt_pk_bf16_f32 v156, v158, v159
	v_cvt_pk_bf16_f32 v157, v160, v161
	v_cvt_pk_bf16_f32 v158, v162, v163
	v_cvt_pk_bf16_f32 v159, v164, v165
	v_cvt_pk_bf16_f32 v160, v166, v167
	v_cvt_pk_bf16_f32 v161, v168, v169
	s_nop 1
	v_mfma_f32_32x32x16_bf16 v[106:121], v[22:25], v[154:157], v[106:121]
	v_mfma_f32_32x32x16_bf16 v[122:137], v[30:33], v[154:157], v[122:137]
	v_mfma_f32_32x32x16_bf16 v[106:121], v[26:29], v[158:161], v[106:121]
	v_mfma_f32_32x32x16_bf16 v[122:137], v[34:37], v[158:161], v[122:137]
	s_lshl_b32 s17, s18, 12
	v_add_u32_e32 v208, s17, v194
	global_load_dwordx4 v[22:25], v208, s[6:7]
	global_load_dwordx4 v[26:29], v208, s[6:7] offset:1024
	global_load_dwordx4 v[30:33], v208, s[6:7] offset:2048
	global_load_dwordx4 v[34:37], v208, s[6:7] offset:3072
	s_add_i32 s16, s16, 1
	s_waitcnt vmcnt(4)
	v_mfma_f32_32x32x16_bf16 v[154:169], v[2:5], v[54:57], 0
	v_mfma_f32_32x32x16_bf16 v[154:169], v[6:9], v[58:61], v[154:169]
	v_mfma_f32_32x32x16_bf16 v[154:169], v[10:13], v[62:65], v[154:169]
	v_mfma_f32_32x32x16_bf16 v[154:169], v[14:17], v[66:69], v[154:169]
	v_mfma_f32_32x32x16_bf16 v[154:169], v[18:21], v[70:73], v[154:169]
	s_nop 7
	s_nop 4
	v_cmp_le_i32_e64 s[34:35], 0, v170
	v_cmp_le_i32_e64 s[36:37], 1, v170
	v_cmp_le_i32_e64 s[38:39], 2, v170
	v_cmp_le_i32_e64 s[40:41], 3, v170
	v_cmp_le_i32_e32 vcc, 8, v170
	v_cndmask_b32_e64 v154, v193, v154, s[34:35]
	v_cndmask_b32_e64 v155, v193, v155, s[36:37]
	v_cndmask_b32_e64 v156, v193, v156, s[38:39]
	v_cndmask_b32_e64 v157, v193, v157, s[40:41]
	v_cndmask_b32_e64 v158, v193, v158, vcc
	v_cmp_le_i32_e64 s[34:35], 9, v170
	v_cmp_le_i32_e64 s[36:37], 10, v170
	v_cmp_le_i32_e64 s[38:39], 11, v170
	v_cmp_le_i32_e64 s[40:41], 16, v170
	v_cmp_le_i32_e32 vcc, 17, v170
	v_cndmask_b32_e64 v159, v193, v159, s[34:35]
	v_cndmask_b32_e64 v160, v193, v160, s[36:37]
	v_cndmask_b32_e64 v161, v193, v161, s[38:39]
	v_cndmask_b32_e64 v162, v193, v162, s[40:41]
	v_cndmask_b32_e64 v163, v193, v163, vcc
	v_cmp_le_i32_e64 s[34:35], 18, v170
	v_cmp_le_i32_e64 s[36:37], 19, v170
	v_cmp_le_i32_e64 s[38:39], 24, v170
	v_cmp_le_i32_e64 s[40:41], 25, v170
	v_cmp_le_i32_e32 vcc, 26, v170
	v_cndmask_b32_e64 v164, v193, v164, s[34:35]
	v_cndmask_b32_e64 v165, v193, v165, s[36:37]
	v_cndmask_b32_e64 v166, v193, v166, s[38:39]
	v_cndmask_b32_e64 v167, v193, v167, s[40:41]
	v_cndmask_b32_e64 v168, v193, v168, vcc
	v_cmp_le_i32_e64 s[34:35], 27, v170
	s_nop 1
	v_cndmask_b32_e64 v169, v193, v169, s[34:35]
	v_max3_f32 v183, v154, v155, v156
	v_max3_f32 v184, v157, v158, v159
	v_max3_f32 v185, v160, v161, v162
	v_max3_f32 v186, v163, v164, v165
	v_max3_f32 v187, v166, v167, v168
	v_max3_f32 v183, v183, v184, v185
	v_max3_f32 v186, v186, v187, v169
	v_max_f32_e32 v183, v183, v186
	v_mov_b32_e32 v184, v183
	s_nop 1
	v_permlane32_swap_b32_e32 v184, v183
	s_waitcnt vmcnt(0)
	v_max_f32_e32 v183, v183, v184
	v_fma_f32 v183, v183, s14, v203
	v_max_f32_e32 v184, v201, v183
	v_sub_f32_e32 v186, v201, v184
	v_exp_f32_e32 v186, v186
	v_mov_b32_e32 v201, v184
	v_sub_f32_e32 v204, v203, v184
	v_fma_f32 v154, v154, s14, v204
	v_exp_f32_e32 v154, v154
	v_fma_f32 v155, v155, s14, v204
	v_exp_f32_e32 v155, v155
	v_fma_f32 v156, v156, s14, v204
	v_exp_f32_e32 v156, v156
	v_fma_f32 v157, v157, s14, v204
	v_exp_f32_e32 v157, v157
	v_fma_f32 v158, v158, s14, v204
	v_exp_f32_e32 v158, v158
	v_fma_f32 v159, v159, s14, v204
	v_exp_f32_e32 v159, v159
	v_fma_f32 v160, v160, s14, v204
	v_exp_f32_e32 v160, v160
	v_fma_f32 v161, v161, s14, v204
	v_exp_f32_e32 v161, v161
	v_fma_f32 v162, v162, s14, v204
	v_exp_f32_e32 v162, v162
	v_fma_f32 v163, v163, s14, v204
	v_exp_f32_e32 v163, v163
	v_fma_f32 v164, v164, s14, v204
	v_exp_f32_e32 v164, v164
	v_fma_f32 v165, v165, s14, v204
	v_exp_f32_e32 v165, v165
	v_fma_f32 v166, v166, s14, v204
	v_exp_f32_e32 v166, v166
	v_fma_f32 v167, v167, s14, v204
	v_exp_f32_e32 v167, v167
	v_fma_f32 v168, v168, s14, v204
	v_exp_f32_e32 v168, v168
	v_fma_f32 v169, v169, s14, v204
	v_exp_f32_e32 v169, v169
	v_mul_f32_e32 v202, v202, v186
	v_pk_mul_f32 v[106:107], v[106:107], v[186:187] op_sel_hi:[1,0]
	v_pk_mul_f32 v[108:109], v[108:109], v[186:187] op_sel_hi:[1,0]
	v_pk_mul_f32 v[110:111], v[110:111], v[186:187] op_sel_hi:[1,0]
	v_pk_mul_f32 v[112:113], v[112:113], v[186:187] op_sel_hi:[1,0]
	v_pk_mul_f32 v[114:115], v[114:115], v[186:187] op_sel_hi:[1,0]
	v_pk_mul_f32 v[116:117], v[116:117], v[186:187] op_sel_hi:[1,0]
	v_pk_mul_f32 v[118:119], v[118:119], v[186:187] op_sel_hi:[1,0]
	v_pk_mul_f32 v[120:121], v[120:121], v[186:187] op_sel_hi:[1,0]
	v_pk_mul_f32 v[122:123], v[122:123], v[186:187] op_sel_hi:[1,0]
	v_pk_mul_f32 v[124:125], v[124:125], v[186:187] op_sel_hi:[1,0]
	v_pk_mul_f32 v[126:127], v[126:127], v[186:187] op_sel_hi:[1,0]
	v_pk_mul_f32 v[128:129], v[128:129], v[186:187] op_sel_hi:[1,0]
	v_pk_mul_f32 v[130:131], v[130:131], v[186:187] op_sel_hi:[1,0]
	v_pk_mul_f32 v[132:133], v[132:133], v[186:187] op_sel_hi:[1,0]
	v_pk_mul_f32 v[134:135], v[134:135], v[186:187] op_sel_hi:[1,0]
	v_pk_mul_f32 v[136:137], v[136:137], v[186:187] op_sel_hi:[1,0]
	v_add_f32_e32 v183, v154, v155
	v_add_f32_e32 v184, v156, v157
	v_add_f32_e32 v185, v158, v159
	v_add_f32_e32 v188, v160, v161
	v_add_f32_e32 v183, v183, v162
	v_add_f32_e32 v184, v184, v163
	v_add_f32_e32 v185, v185, v164
	v_add_f32_e32 v188, v188, v165
	v_add_f32_e32 v183, v183, v166
	v_add_f32_e32 v184, v184, v167
	v_add_f32_e32 v185, v185, v168
	v_add_f32_e32 v188, v188, v169
	v_add_f32_e32 v183, v183, v184
	v_add_f32_e32 v185, v185, v188
	v_add_f32_e32 v183, v183, v185
	v_add_f32_e32 v202, v202, v183
	v_cvt_pk_bf16_f32 v154, v154, v155
	v_cvt_pk_bf16_f32 v155, v156, v157
	v_cvt_pk_bf16_f32 v156, v158, v159
	v_cvt_pk_bf16_f32 v157, v160, v161
	v_cvt_pk_bf16_f32 v158, v162, v163
	v_cvt_pk_bf16_f32 v159, v164, v165
	v_cvt_pk_bf16_f32 v160, v166, v167
	v_cvt_pk_bf16_f32 v161, v168, v169
	s_nop 1
	v_mfma_f32_32x32x16_bf16 v[106:121], v[22:25], v[154:157], v[106:121]
	v_mfma_f32_32x32x16_bf16 v[122:137], v[30:33], v[154:157], v[122:137]
	v_mfma_f32_32x32x16_bf16 v[106:121], v[26:29], v[158:161], v[106:121]
	v_mfma_f32_32x32x16_bf16 v[122:137], v[34:37], v[158:161], v[122:137]
	s_nop 7
	s_nop 7
	v_mov_b32_e32 v184, v198
	s_nop 1
	v_permlane32_swap_b32_e32 v184, v198
	v_add_f32_e32 v198, v198, v184
	v_rcp_f32_e32 v186, v198
	s_nop 0
	v_fma_f32 v184, -v198, v186, 1.0
	v_fma_f32 v186, v186, v184, v186
	v_pk_mul_f32 v[74:75], v[74:75], v[186:187] op_sel_hi:[1,0]
	v_pk_mul_f32 v[76:77], v[76:77], v[186:187] op_sel_hi:[1,0]
	v_pk_mul_f32 v[78:79], v[78:79], v[186:187] op_sel_hi:[1,0]
	v_pk_mul_f32 v[80:81], v[80:81], v[186:187] op_sel_hi:[1,0]
	v_pk_mul_f32 v[82:83], v[82:83], v[186:187] op_sel_hi:[1,0]
	v_pk_mul_f32 v[84:85], v[84:85], v[186:187] op_sel_hi:[1,0]
	v_pk_mul_f32 v[86:87], v[86:87], v[186:187] op_sel_hi:[1,0]
	v_pk_mul_f32 v[88:89], v[88:89], v[186:187] op_sel_hi:[1,0]
	v_pk_mul_f32 v[90:91], v[90:91], v[186:187] op_sel_hi:[1,0]
	v_pk_mul_f32 v[92:93], v[92:93], v[186:187] op_sel_hi:[1,0]
	v_pk_mul_f32 v[94:95], v[94:95], v[186:187] op_sel_hi:[1,0]
	v_pk_mul_f32 v[96:97], v[96:97], v[186:187] op_sel_hi:[1,0]
	v_pk_mul_f32 v[98:99], v[98:99], v[186:187] op_sel_hi:[1,0]
	v_pk_mul_f32 v[100:101], v[100:101], v[186:187] op_sel_hi:[1,0]
	v_pk_mul_f32 v[102:103], v[102:103], v[186:187] op_sel_hi:[1,0]
	v_pk_mul_f32 v[104:105], v[104:105], v[186:187] op_sel_hi:[1,0]
	v_cvt_pk_bf16_f32 v74, v74, v75
	v_cvt_pk_bf16_f32 v75, v76, v77
	global_store_dwordx2 v205, v[74:75], s[12:13]
	v_cvt_pk_bf16_f32 v78, v78, v79
	v_cvt_pk_bf16_f32 v79, v80, v81
	global_store_dwordx2 v205, v[78:79], s[12:13] offset:16
	v_cvt_pk_bf16_f32 v82, v82, v83
	v_cvt_pk_bf16_f32 v83, v84, v85
	global_store_dwordx2 v205, v[82:83], s[12:13] offset:32
	v_cvt_pk_bf16_f32 v86, v86, v87
	v_cvt_pk_bf16_f32 v87, v88, v89
	global_store_dwordx2 v205, v[86:87], s[12:13] offset:48
	v_cvt_pk_bf16_f32 v90, v90, v91
	v_cvt_pk_bf16_f32 v91, v92, v93
	global_store_dwordx2 v205, v[90:91], s[12:13] offset:64
	v_cvt_pk_bf16_f32 v94, v94, v95
	v_cvt_pk_bf16_f32 v95, v96, v97
	global_store_dwordx2 v205, v[94:95], s[12:13] offset:80
	v_cvt_pk_bf16_f32 v98, v98, v99
	v_cvt_pk_bf16_f32 v99, v100, v101
	global_store_dwordx2 v205, v[98:99], s[12:13] offset:96
	v_cvt_pk_bf16_f32 v102, v102, v103
	v_cvt_pk_bf16_f32 v103, v104, v105
	global_store_dwordx2 v205, v[102:103], s[12:13] offset:112
	v_mov_b32_e32 v184, v202
	s_nop 1
	v_permlane32_swap_b32_e32 v184, v202
	v_add_f32_e32 v202, v202, v184
	v_rcp_f32_e32 v186, v202
	s_nop 0
	v_fma_f32 v184, -v202, v186, 1.0
	v_fma_f32 v186, v186, v184, v186
	v_pk_mul_f32 v[106:107], v[106:107], v[186:187] op_sel_hi:[1,0]
	v_pk_mul_f32 v[108:109], v[108:109], v[186:187] op_sel_hi:[1,0]
	v_pk_mul_f32 v[110:111], v[110:111], v[186:187] op_sel_hi:[1,0]
	v_pk_mul_f32 v[112:113], v[112:113], v[186:187] op_sel_hi:[1,0]
	v_pk_mul_f32 v[114:115], v[114:115], v[186:187] op_sel_hi:[1,0]
	v_pk_mul_f32 v[116:117], v[116:117], v[186:187] op_sel_hi:[1,0]
	v_pk_mul_f32 v[118:119], v[118:119], v[186:187] op_sel_hi:[1,0]
	v_pk_mul_f32 v[120:121], v[120:121], v[186:187] op_sel_hi:[1,0]
	v_pk_mul_f32 v[122:123], v[122:123], v[186:187] op_sel_hi:[1,0]
	v_pk_mul_f32 v[124:125], v[124:125], v[186:187] op_sel_hi:[1,0]
	v_pk_mul_f32 v[126:127], v[126:127], v[186:187] op_sel_hi:[1,0]
	v_pk_mul_f32 v[128:129], v[128:129], v[186:187] op_sel_hi:[1,0]
	v_pk_mul_f32 v[130:131], v[130:131], v[186:187] op_sel_hi:[1,0]
	v_pk_mul_f32 v[132:133], v[132:133], v[186:187] op_sel_hi:[1,0]
	v_pk_mul_f32 v[134:135], v[134:135], v[186:187] op_sel_hi:[1,0]
	v_pk_mul_f32 v[136:137], v[136:137], v[186:187] op_sel_hi:[1,0]
	v_cvt_pk_bf16_f32 v106, v106, v107
	v_cvt_pk_bf16_f32 v107, v108, v109
	global_store_dwordx2 v206, v[106:107], s[12:13]
	v_cvt_pk_bf16_f32 v110, v110, v111
	v_cvt_pk_bf16_f32 v111, v112, v113
	global_store_dwordx2 v206, v[110:111], s[12:13] offset:16
	v_cvt_pk_bf16_f32 v114, v114, v115
	v_cvt_pk_bf16_f32 v115, v116, v117
	global_store_dwordx2 v206, v[114:115], s[12:13] offset:32
	v_cvt_pk_bf16_f32 v118, v118, v119
	v_cvt_pk_bf16_f32 v119, v120, v121
	global_store_dwordx2 v206, v[118:119], s[12:13] offset:48
	v_cvt_pk_bf16_f32 v122, v122, v123
	v_cvt_pk_bf16_f32 v123, v124, v125
	global_store_dwordx2 v206, v[122:123], s[12:13] offset:64
	v_cvt_pk_bf16_f32 v126, v126, v127
	v_cvt_pk_bf16_f32 v127, v128, v129
	global_store_dwordx2 v206, v[126:127], s[12:13] offset:80
	v_cvt_pk_bf16_f32 v130, v130, v131
	v_cvt_pk_bf16_f32 v131, v132, v133
	global_store_dwordx2 v206, v[130:131], s[12:13] offset:96
	v_cvt_pk_bf16_f32 v134, v134, v135
	v_cvt_pk_bf16_f32 v135, v136, v137
	global_store_dwordx2 v206, v[134:135], s[12:13] offset:112
	s_waitcnt vmcnt(0)
	s_add_i32 s22, s22, s68
	s_cmpk_lt_i32 s22, 0x800
	s_cbranch_scc1 .Lfox_outer
	v_lshlrev_b32_e32 v2, 2, v220
	v_add_u32_e32 v3, 0x10000, v2
	ds_read_b32 v146, v2 offset:0
	ds_read_b32 v147, v2 offset:2048
	ds_read_b32 v148, v2 offset:4096
	ds_read_b32 v149, v2 offset:6144
	ds_read_b32 v150, v2 offset:8192
	ds_read_b32 v151, v2 offset:10240
	ds_read_b32 v152, v2 offset:12288
	ds_read_b32 v153, v2 offset:14336
	ds_read_b32 v154, v2 offset:16384
	ds_read_b32 v155, v2 offset:18432
	ds_read_b32 v156, v2 offset:20480
	ds_read_b32 v157, v2 offset:22528
	ds_read_b32 v158, v2 offset:24576
	ds_read_b32 v159, v2 offset:26624
	ds_read_b32 v160, v2 offset:28672
	ds_read_b32 v161, v2 offset:30720
	ds_read_b32 v162, v2 offset:32768
	ds_read_b32 v163, v2 offset:34816
	ds_read_b32 v164, v2 offset:36864
	ds_read_b32 v165, v2 offset:38912
	ds_read_b32 v166, v2 offset:40960
	ds_read_b32 v167, v2 offset:43008
	ds_read_b32 v168, v2 offset:45056
	ds_read_b32 v169, v2 offset:47104
	ds_read_b32 v170, v2 offset:49152
	ds_read_b32 v183, v2 offset:51200
	ds_read_b32 v184, v2 offset:53248
	ds_read_b32 v185, v2 offset:55296
	ds_read_b32 v186, v2 offset:57344
	ds_read_b32 v187, v2 offset:59392
	ds_read_b32 v188, v2 offset:61440
	ds_read_b32 v189, v2 offset:63488
	ds_read_b32 v190, v3 offset:0
	ds_read_b32 v191, v3 offset:2048
	ds_read_b32 v192, v3 offset:4096
	ds_read_b32 v193, v3 offset:6144
	ds_read_b32 v194, v3 offset:8192
	ds_read_b32 v195, v3 offset:10240
	ds_read_b32 v196, v3 offset:12288
	ds_read_b32 v197, v3 offset:14336
	ds_read_b32 v198, v3 offset:16384
	ds_read_b32 v199, v3 offset:18432
	ds_read_b32 v200, v3 offset:20480
	ds_read_b32 v201, v3 offset:22528
	ds_read_b32 v202, v3 offset:24576
	ds_read_b32 v203, v3 offset:26624
	ds_read_b32 v204, v3 offset:28672
	ds_read_b32 v205, v3 offset:30720
	ds_read_b32 v206, v3 offset:32768
	ds_read_b32 v207, v3 offset:34816
	ds_read_b32 v208, v3 offset:36864
	ds_read_b32 v209, v3 offset:38912
	ds_read_b32 v210, v3 offset:40960
	ds_read_b32 v211, v3 offset:43008
	ds_read_b32 v212, v3 offset:45056
	ds_read_b32 v213, v3 offset:47104
	ds_read_b32 v214, v3 offset:49152
	ds_read_b32 v215, v3 offset:51200
	ds_read_b32 v216, v3 offset:53248
	v_lshrrev_b32_e32 v2, 6, v220
	v_lshlrev_b32_e32 v2, 8, v2
	v_add_u32_e32 v2, 0x1d800, v2
	ds_read_b32 v4, v2 offset:0
	ds_read_b32 v5, v2 offset:4
	ds_read_b32 v6, v2 offset:8
	ds_read_b32 v7, v2 offset:12
	ds_read_b32 v8, v2 offset:16
	ds_read_b32 v9, v2 offset:20
	ds_read_b32 v10, v2 offset:24
	ds_read_b32 v11, v2 offset:28
	ds_read_b32 v12, v2 offset:32
	ds_read_b32 v13, v2 offset:36
	ds_read_b32 v14, v2 offset:40
	ds_read_b32 v15, v2 offset:44
	ds_read_b32 v16, v2 offset:48
	ds_read_b32 v17, v2 offset:52
	ds_read_b32 v18, v2 offset:56
	ds_read_b32 v19, v2 offset:60
	ds_read_b32 v20, v2 offset:64
	ds_read_b32 v21, v2 offset:68
	ds_read_b32 v22, v2 offset:72
	ds_read_b32 v23, v2 offset:76
	ds_read_b32 v24, v2 offset:80
	ds_read_b32 v25, v2 offset:84
	ds_read_b32 v26, v2 offset:88
	ds_read_b32 v27, v2 offset:92
	ds_read_b32 v28, v2 offset:96
	ds_read_b32 v29, v2 offset:100
	ds_read_b32 v30, v2 offset:104
	ds_read_b32 v31, v2 offset:108
	ds_read_b32 v32, v2 offset:112
	ds_read_b32 v33, v2 offset:116
	ds_read_b32 v34, v2 offset:120
	ds_read_b32 v35, v2 offset:124
	ds_read_b32 v36, v2 offset:128
	ds_read_b32 v37, v2 offset:132
	ds_read_b32 v38, v2 offset:136
	ds_read_b32 v39, v2 offset:140
	ds_read_b32 v40, v2 offset:144
	ds_read_b32 v41, v2 offset:148
	ds_read_b32 v42, v2 offset:152
	ds_read_b32 v43, v2 offset:156
	ds_read_b32 v44, v2 offset:160
	ds_read_b32 v45, v2 offset:164
	s_waitcnt lgkmcnt(0)
	v_readfirstlane_b32 s2, v4
	v_readfirstlane_b32 s3, v5
	v_readfirstlane_b32 s4, v6
	v_readfirstlane_b32 s5, v7
	v_readfirstlane_b32 s6, v8
	v_readfirstlane_b32 s7, v9
	v_readfirstlane_b32 s8, v10
	v_readfirstlane_b32 s9, v11
	v_readfirstlane_b32 s10, v12
	v_readfirstlane_b32 s11, v13
	v_readfirstlane_b32 s12, v14
	v_readfirstlane_b32 s13, v15
	v_readfirstlane_b32 s14, v16
	v_readfirstlane_b32 s15, v17
	v_readfirstlane_b32 s16, v18
	v_readfirstlane_b32 s17, v19
	v_readfirstlane_b32 s18, v20
	v_readfirstlane_b32 s19, v21
	v_readfirstlane_b32 s20, v22
	v_readfirstlane_b32 s21, v23
	v_readfirstlane_b32 s22, v24
	v_readfirstlane_b32 s23, v25
	v_readfirstlane_b32 s24, v26
	v_readfirstlane_b32 s25, v27
	v_readfirstlane_b32 s26, v28
	v_readfirstlane_b32 s27, v29
	v_readfirstlane_b32 s28, v30
	v_readfirstlane_b32 s29, v31
	v_readfirstlane_b32 s30, v32
	v_readfirstlane_b32 s31, v33
	v_readfirstlane_b32 s34, v34
	v_readfirstlane_b32 s35, v35
	v_readfirstlane_b32 s36, v36
	v_readfirstlane_b32 s37, v37
	v_readfirstlane_b32 s38, v38
	v_readfirstlane_b32 s39, v39
	v_readfirstlane_b32 s40, v40
	v_readfirstlane_b32 s41, v41
	v_readfirstlane_b32 s42, v42
	v_readfirstlane_b32 s43, v43
	v_readfirstlane_b32 s44, v44
	v_readfirstlane_b32 s45, v45
